# static priority per phase type: waves 4-7 raised in the GEMM phases, waves 0-3 in the others
# baseline (speedup 1.0000x reference)
.LBB0_241:
	v_readfirstlane_b32 s98, v0
	s_nop 3
	s_cmpk_ge_u32 s98, 0x100
	s_cbranch_scc1 .Lpr_hi1
	s_setprio 0
	s_branch .Lpr_dn1
.Lpr_hi1:
	s_setprio 1

.LBB0_753:
	v_readfirstlane_b32 s98, v0
	s_nop 3
	s_cmpk_ge_u32 s98, 0x100
	s_cbranch_scc0 .Lpr_hi2
	s_setprio 0
	s_branch .Lpr_dn2
